# r6_nt plus nt hint on the read-once split-K partial-tile loads in reduce_tail
# speedup vs baseline: 1.0049x; 1.0049x over previous
; template <class Order>
; __device__ __forceinline__ void reduce_tail(const Order& S, const float* PART, const float* gate, const XBuf xin, const XBuf xout, int lane, int wave, int G, int bx) {
;     ...
;         for (int rl = r0 + wave * 2 + (lane >> 5); rl < r0 + rows; rl += 16) { const int row = pm * 256 + rl, col = pn * 256 + c8;
;             f32x4 s0 = {0.f, 0.f, 0.f, 0.f}, s1 = {0.f, 0.f, 0.f, 0.f};
;             for (int p = 0; p < S.split; ++p) { const float* pp = PART + ((size_t)((it / S.split) * S.split + p) * 256 + rl) * 256 + c8; s0 += *(const f32x4*)pp; s1 += *(const f32x4*)(pp + 4); }
;             const float* gp = gate + (size_t)batch_of(row) * NMOD + col; const f32x4 g0 = *(const f32x4*)gp, g1 = *(const f32x4*)(gp + 4);
.LBB0_746:
	v_ashrrev_i32_e32 v19, 31, v18
	v_lshlrev_b64 v[0:1], 10, v[18:19]
	v_mov_b32_e32 v32, 0
	v_lshl_add_u64 v[0:1], v[16:17], 0, v[0:1]
	s_mov_b32 s12, s22
	s_mov_b32 s2, s44
	v_mov_b32_e32 v33, v32
	v_mov_b32_e32 v28, v32
	v_mov_b32_e32 v29, v32
	v_mov_b32_e32 v30, v32
	v_mov_b32_e32 v31, v32
	v_mov_b32_e32 v26, v32
	v_mov_b32_e32 v27, v32
	s_cmp_eq_u32 s2, 4
	s_cbranch_scc0 .LBB0_747
	s_ashr_i32 s13, s12, 31
	s_lshl_b64 s[26:27], s[12:13], 18
	v_lshl_add_u64 v[6:7], v[0:1], 0, s[26:27]
	global_load_dwordx4 v[2:5], v[6:7], off nt
	global_load_dwordx4 v[40:43], v[6:7], off offset:16 nt
	s_add_u32 s26, s26, 0x40000
	s_addc_u32 s27, s27, 0
	v_lshl_add_u64 v[6:7], v[0:1], 0, s[26:27]
	global_load_dwordx4 v[44:47], v[6:7], off nt
	global_load_dwordx4 v[48:51], v[6:7], off offset:16 nt
	s_add_u32 s26, s26, 0x40000
	s_addc_u32 s27, s27, 0
	v_lshl_add_u64 v[6:7], v[0:1], 0, s[26:27]
	global_load_dwordx4 v[52:55], v[6:7], off nt
	global_load_dwordx4 v[56:59], v[6:7], off offset:16 nt
	s_add_u32 s26, s26, 0x40000
	s_addc_u32 s27, s27, 0
	v_lshl_add_u64 v[6:7], v[0:1], 0, s[26:27]
	global_load_dwordx4 v[60:63], v[6:7], off nt
	global_load_dwordx4 v[64:67], v[6:7], off offset:16 nt
	s_add_i32 s12, s12, 4
	s_mov_b32 s2, 0
	s_waitcnt vmcnt(0)
	v_pk_add_f32 v[28:29], v[28:29], v[4:5]
	v_pk_add_f32 v[32:33], v[32:33], v[2:3]
	v_pk_add_f32 v[26:27], v[26:27], v[42:43]
	v_pk_add_f32 v[30:31], v[30:31], v[40:41]
	v_pk_add_f32 v[28:29], v[28:29], v[46:47]
	v_pk_add_f32 v[32:33], v[32:33], v[44:45]
	v_pk_add_f32 v[26:27], v[26:27], v[50:51]
	v_pk_add_f32 v[30:31], v[30:31], v[48:49]
	v_pk_add_f32 v[28:29], v[28:29], v[54:55]
	v_pk_add_f32 v[32:33], v[32:33], v[52:53]
	v_pk_add_f32 v[26:27], v[26:27], v[58:59]
	v_pk_add_f32 v[30:31], v[30:31], v[56:57]
	v_pk_add_f32 v[28:29], v[28:29], v[62:63]
	v_pk_add_f32 v[32:33], v[32:33], v[60:61]
	v_pk_add_f32 v[26:27], v[26:27], v[66:67]
	v_pk_add_f32 v[30:31], v[30:31], v[64:65]
	s_branch .Lrt_done
